# wave_sum butterflies in norm / mla_prep / final norm via permlane swaps and DPP row rotates instead of LDS shuffles
# baseline (speedup 1.0000x reference)
.LBB0_431:
	s_mov_b64 s[12:13], s[68:69]
	s_mov_b64 s[14:15], s[68:69]
	s_mov_b64 s[10:11], s[68:69]
	s_mov_b64 s[8:9], s[68:69]
	v_mov_b32_e32 v0, v196
	v_mov_b32_e32 v1, v196
	v_readlane_b32 s0, v251, 20
	v_ashrrev_i32_e32 v10, 6, v1
	s_mul_i32 s96, s22, 0xc00
	v_add_u32_e32 v14, s0, v10
	v_cmp_gt_i32_e32 vcc, s73, v14
	v_readlane_b32 s1, v251, 21
	s_and_saveexec_b64 s[4:5], vcc
	s_cbranch_execz .LBB0_434
	s_load_dwordx2 s[0:1], s[14:15], 0xb8
	s_nop 0
	s_load_dwordx2 s[12:13], s[12:13], 0x28
	v_readlane_b32 s14, v251, 53
	v_readlane_b32 s15, v251, 54
	s_lshl_b64 s[14:15], s[14:15], 2
	s_load_dwordx2 s[10:11], s[10:11], 0xb8
	s_waitcnt lgkmcnt(0)
	s_add_u32 s16, s0, s14
	s_addc_u32 s17, s1, s15
	s_lshl_b64 s[0:1], s[96:97], 2
	s_add_u32 s16, s16, s0
	s_addc_u32 s17, s17, s1
	s_add_u32 s10, s10, s14
	s_addc_u32 s11, s11, s15
	s_add_u32 s0, s10, s0
	v_readlane_b32 s10, v250, 10
	s_mul_i32 s10, s10, 3
	s_addc_u32 s1, s11, s1
	s_add_i32 s10, s22, s10
	s_lshl_b32 s10, s10, 10
	s_mov_b32 s11, s97
	s_lshl_b64 s[10:11], s[10:11], 2
	v_and_b32_e32 v21, 63, v0
	s_add_u32 s10, s12, s10
	s_addc_u32 s11, s13, s11
	v_lshlrev_b32_e32 v92, 4, v21
	global_load_dwordx4 v[0:3], v92, s[10:11]
	v_lshl_add_u64 v[6:7], s[0:1], 0, v[92:93]
	s_mov_b64 s[0:1], 0x1000
	v_cmp_lt_i32_e32 vcc, v204, v198
	v_lshl_add_u64 v[6:7], v[6:7], 0, s[0:1]
	v_readlane_b32 s0, v251, 20
	s_load_dwordx2 s[8:9], s[8:9], 0xb8
	v_cndmask_b32_e32 v4, v197, v204, vcc
	v_cmp_lt_i32_e32 vcc, v205, v198
	v_ashrrev_i32_e32 v11, 31, v10
	v_readlane_b32 s1, v251, 21
	v_lshlrev_b32_e32 v15, 2, v4
	v_cndmask_b32_e32 v4, v197, v205, vcc
	v_cmp_lt_i32_e32 vcc, v203, v198
	v_lshl_add_u64 v[12:13], s[0:1], 0, v[10:11]
	v_lshlrev_b32_e32 v16, 2, v4
	v_cndmask_b32_e32 v4, v197, v203, vcc
	v_cmp_lt_i32_e32 vcc, v202, v198
	v_lshlrev_b64 v[10:11], 12, v[12:13]
	v_lshlrev_b32_e32 v17, 2, v4
	v_cndmask_b32_e32 v4, v197, v202, vcc
	v_cmp_lt_i32_e32 vcc, v201, v198
	v_or_b32_e32 v10, v10, v92
	v_lshlrev_b64 v[12:13], 11, v[12:13]
	v_lshlrev_b32_e32 v18, 2, v4
	v_cndmask_b32_e32 v4, v197, v201, vcc
	v_cmp_lt_i32_e32 vcc, v199, v198
	v_lshl_add_u64 v[10:11], s[6:7], 0, v[10:11]
	s_mov_b64 s[0:1], 0x800
	v_lshl_or_b32 v12, v21, 3, v12
	v_lshlrev_b32_e32 v19, 2, v4
	v_cndmask_b32_e32 v4, v197, v199, vcc
	v_lshl_add_u64 v[10:11], v[10:11], 0, s[0:1]
	s_waitcnt lgkmcnt(0)
	v_lshl_add_u64 v[12:13], s[8:9], 0, v[12:13]
	s_mov_b64 s[0:1], 0xe46c400
	v_lshlrev_b32_e32 v20, 2, v4
	v_lshl_add_u64 v[4:5], s[10:11], 0, v[92:93]
	v_lshl_add_u64 v[8:9], s[16:17], 0, v[92:93]
	v_lshl_add_u64 v[12:13], v[12:13], 0, s[0:1]
	s_mov_b64 s[6:7], 0
	s_cmp_lg_u32 s30, 0x100
	s_cbranch_scc1 .LBB0_433
	v_ashrrev_i32_e32 v21, 11, v14
	v_mul_hi_i32_i24_e32 v23, 0x2400, v21
	v_mul_i32_i24_e32 v22, 0x2400, v21
	v_lshlrev_b64 v[22:23], 2, v[22:23]
	v_lshl_add_u64 v[6:7], v[6:7], 0, v[22:23]
	v_lshl_add_u64 v[8:9], v[8:9], 0, v[22:23]
	global_load_dwordx4 v[24:27], v[6:7], off
	global_load_dwordx4 v[28:31], v[6:7], off offset:1024
	global_load_dwordx4 v[32:35], v[6:7], off offset:2048
	global_load_dwordx4 v[36:39], v[6:7], off offset:3072
	global_load_dwordx4 v[52:55], v[8:9], off
	global_load_dwordx4 v[56:59], v[8:9], off offset:1024
	global_load_dwordx4 v[60:63], v[8:9], off offset:2048
	global_load_dwordx4 v[64:67], v[8:9], off offset:3072
	global_load_dwordx4 v[40:43], v[4:5], off offset:1024
	global_load_dwordx4 v[44:47], v[4:5], off offset:2048
	global_load_dwordx4 v[48:51], v[4:5], off offset:3072
	v_lshl_add_u64 v[22:23], v[10:11], 0, s[34:35]
	global_load_dwordx4 v[96:99], v[10:11], off offset:-2048
	global_load_dwordx4 v[100:103], v[10:11], off offset:-1024
	global_load_dwordx4 v[104:107], v[10:11], off
	global_load_dwordx4 v[108:111], v[10:11], off offset:1024
	v_lshl_add_u64 v[68:69], v[22:23], 0, s[34:35]
	global_load_dwordx4 v[112:115], v[22:23], off offset:-2048
	global_load_dwordx4 v[116:119], v[22:23], off offset:-1024
	global_load_dwordx4 v[120:123], v[22:23], off
	global_load_dwordx4 v[124:127], v[22:23], off offset:1024
	v_lshl_add_u64 v[70:71], v[68:69], 0, s[34:35]
	global_load_dwordx4 v[128:131], v[68:69], off offset:-2048
	global_load_dwordx4 v[132:135], v[68:69], off offset:-1024
	global_load_dwordx4 v[136:139], v[68:69], off
	global_load_dwordx4 v[140:143], v[68:69], off offset:1024
	v_lshl_add_u64 v[10:11], v[70:71], 0, s[34:35]
	global_load_dwordx4 v[160:163], v[70:71], off offset:-2048
	global_load_dwordx4 v[164:167], v[70:71], off offset:-1024
	global_load_dwordx4 v[168:171], v[70:71], off
	global_load_dwordx4 v[172:175], v[70:71], off offset:1024
	v_lshl_add_u64 v[22:23], v[10:11], 0, s[34:35]
	global_load_dwordx4 v[176:179], v[10:11], off offset:-2048
	global_load_dwordx4 v[180:183], v[10:11], off offset:-1024
	global_load_dwordx4 v[184:187], v[10:11], off
	global_load_dwordx4 v[188:191], v[10:11], off offset:1024
	v_lshl_add_u64 v[68:69], v[22:23], 0, s[34:35]
	global_load_dwordx4 v[214:217], v[22:23], off offset:-2048
	global_load_dwordx4 v[218:221], v[22:23], off offset:-1024
	global_load_dwordx4 v[222:225], v[22:23], off
	global_load_dwordx4 v[226:229], v[22:23], off offset:1024
	v_lshl_add_u64 v[70:71], v[68:69], 0, s[34:35]
	global_load_dwordx4 v[76:79], v[68:69], off offset:-2048
	global_load_dwordx4 v[80:83], v[68:69], off offset:-1024
	global_load_dwordx4 v[84:87], v[68:69], off
	global_load_dwordx4 v[88:91], v[68:69], off offset:1024
	global_load_dwordx4 v[144:147], v[70:71], off offset:-2048
	global_load_dwordx4 v[148:151], v[70:71], off offset:-1024
	global_load_dwordx4 v[152:155], v[70:71], off
	global_load_dwordx4 v[230:233], v[70:71], off offset:1024
	s_waitcnt vmcnt(16)
	v_add_f32_e32 v24, 1.0, v24
	v_add_f32_e32 v25, 1.0, v25
	v_add_f32_e32 v26, 1.0, v26
	v_add_f32_e32 v27, 1.0, v27
	v_add_f32_e32 v28, 1.0, v28
	v_add_f32_e32 v29, 1.0, v29
	v_add_f32_e32 v30, 1.0, v30
	v_add_f32_e32 v31, 1.0, v31
	v_add_f32_e32 v32, 1.0, v32
	v_add_f32_e32 v33, 1.0, v33
	v_add_f32_e32 v34, 1.0, v34
	v_add_f32_e32 v35, 1.0, v35
	v_add_f32_e32 v36, 1.0, v36
	v_add_f32_e32 v37, 1.0, v37
	v_add_f32_e32 v38, 1.0, v38
	v_add_f32_e32 v39, 1.0, v39
	v_mul_f32_e32 v4, v96, v96
	v_fmac_f32_e32 v4, v97, v97
	v_fmac_f32_e32 v4, v98, v98
	v_fmac_f32_e32 v4, v99, v99
	v_fmac_f32_e32 v4, v100, v100
	v_fmac_f32_e32 v4, v101, v101
	v_fmac_f32_e32 v4, v102, v102
	v_fmac_f32_e32 v4, v103, v103
	v_fmac_f32_e32 v4, v104, v104
	v_fmac_f32_e32 v4, v105, v105
	v_fmac_f32_e32 v4, v106, v106
	v_fmac_f32_e32 v4, v107, v107
	v_fmac_f32_e32 v4, v108, v108
	v_fmac_f32_e32 v4, v109, v109
	v_fmac_f32_e32 v4, v110, v110
	v_fmac_f32_e32 v4, v111, v111
	v_mul_f32_e32 v5, v112, v112
	v_fmac_f32_e32 v5, v113, v113
	v_fmac_f32_e32 v5, v114, v114
	v_fmac_f32_e32 v5, v115, v115
	v_fmac_f32_e32 v5, v116, v116
	v_fmac_f32_e32 v5, v117, v117
	v_fmac_f32_e32 v5, v118, v118
	v_fmac_f32_e32 v5, v119, v119
	v_fmac_f32_e32 v5, v120, v120
	v_fmac_f32_e32 v5, v121, v121
	v_fmac_f32_e32 v5, v122, v122
	v_fmac_f32_e32 v5, v123, v123
	v_fmac_f32_e32 v5, v124, v124
	v_fmac_f32_e32 v5, v125, v125
	v_fmac_f32_e32 v5, v126, v126
	v_fmac_f32_e32 v5, v127, v127
	v_mul_f32_e32 v6, v128, v128
	v_fmac_f32_e32 v6, v129, v129
	v_fmac_f32_e32 v6, v130, v130
	v_fmac_f32_e32 v6, v131, v131
	v_fmac_f32_e32 v6, v132, v132
	v_fmac_f32_e32 v6, v133, v133
	v_fmac_f32_e32 v6, v134, v134
	v_fmac_f32_e32 v6, v135, v135
	v_fmac_f32_e32 v6, v136, v136
	v_fmac_f32_e32 v6, v137, v137
	v_fmac_f32_e32 v6, v138, v138
	v_fmac_f32_e32 v6, v139, v139
	v_fmac_f32_e32 v6, v140, v140
	v_fmac_f32_e32 v6, v141, v141
	v_fmac_f32_e32 v6, v142, v142
	v_fmac_f32_e32 v6, v143, v143
	v_mul_f32_e32 v7, v160, v160
	v_fmac_f32_e32 v7, v161, v161
	v_fmac_f32_e32 v7, v162, v162
	v_fmac_f32_e32 v7, v163, v163
	v_fmac_f32_e32 v7, v164, v164
	v_fmac_f32_e32 v7, v165, v165
	v_fmac_f32_e32 v7, v166, v166
	v_fmac_f32_e32 v7, v167, v167
	v_fmac_f32_e32 v7, v168, v168
	v_fmac_f32_e32 v7, v169, v169
	v_fmac_f32_e32 v7, v170, v170
	v_fmac_f32_e32 v7, v171, v171
	v_fmac_f32_e32 v7, v172, v172
	v_fmac_f32_e32 v7, v173, v173
	v_fmac_f32_e32 v7, v174, v174
	v_fmac_f32_e32 v7, v175, v175
	v_mov_b32_e32 v8, v4
	s_nop 1
	v_permlane32_swap_b32_e32 v8, v4
	v_mov_b32_e32 v9, v5
	s_nop 1
	v_permlane32_swap_b32_e32 v9, v5
	v_mov_b32_e32 v14, v6
	s_nop 1
	v_permlane32_swap_b32_e32 v14, v6
	v_mov_b32_e32 v21, v7
	s_nop 1
	v_permlane32_swap_b32_e32 v21, v7
	s_waitcnt lgkmcnt(3)
	v_add_f32_e32 v4, v4, v8
	s_waitcnt lgkmcnt(2)
	v_add_f32_e32 v5, v5, v9
	s_waitcnt lgkmcnt(1)
	v_add_f32_e32 v6, v6, v14
	s_waitcnt lgkmcnt(0)
	v_add_f32_e32 v7, v7, v21
	v_mov_b32_e32 v8, v4
	s_nop 1
	v_permlane16_swap_b32_e32 v8, v4
	v_mov_b32_e32 v9, v5
	s_nop 1
	v_permlane16_swap_b32_e32 v9, v5
	v_mov_b32_e32 v14, v6
	s_nop 1
	v_permlane16_swap_b32_e32 v14, v6
	v_mov_b32_e32 v21, v7
	s_nop 1
	v_permlane16_swap_b32_e32 v21, v7
	s_waitcnt lgkmcnt(3)
	v_add_f32_e32 v4, v4, v8
	s_waitcnt lgkmcnt(2)
	v_add_f32_e32 v5, v5, v9
	s_waitcnt lgkmcnt(1)
	v_add_f32_e32 v6, v6, v14
	s_waitcnt lgkmcnt(0)
	v_add_f32_e32 v7, v7, v21
	s_nop 1
	v_mov_b32_dpp v8, v4 row_ror:8 row_mask:0xf bank_mask:0xf
	s_nop 1
	v_mov_b32_dpp v9, v5 row_ror:8 row_mask:0xf bank_mask:0xf
	s_nop 1
	v_mov_b32_dpp v14, v6 row_ror:8 row_mask:0xf bank_mask:0xf
	s_nop 1
	v_mov_b32_dpp v21, v7 row_ror:8 row_mask:0xf bank_mask:0xf
	s_waitcnt lgkmcnt(3)
	v_add_f32_e32 v4, v4, v8
	s_waitcnt lgkmcnt(2)
	v_add_f32_e32 v5, v5, v9
	s_waitcnt lgkmcnt(1)
	v_add_f32_e32 v6, v6, v14
	s_waitcnt lgkmcnt(0)
	v_add_f32_e32 v7, v7, v21
	s_nop 1
	v_mov_b32_dpp v8, v4 row_ror:4 row_mask:0xf bank_mask:0xf
	s_nop 1
	v_mov_b32_dpp v9, v5 row_ror:4 row_mask:0xf bank_mask:0xf
	s_nop 1
	v_mov_b32_dpp v14, v6 row_ror:4 row_mask:0xf bank_mask:0xf
	s_nop 1
	v_mov_b32_dpp v21, v7 row_ror:4 row_mask:0xf bank_mask:0xf
	s_waitcnt lgkmcnt(3)
	v_add_f32_e32 v4, v4, v8
	s_waitcnt lgkmcnt(2)
	v_add_f32_e32 v5, v5, v9
	s_waitcnt lgkmcnt(1)
	v_add_f32_e32 v6, v6, v14
	s_waitcnt lgkmcnt(0)
	v_add_f32_e32 v7, v7, v21
	s_nop 1
	v_mov_b32_dpp v8, v4 row_ror:2 row_mask:0xf bank_mask:0xf
	s_nop 1
	v_mov_b32_dpp v9, v5 row_ror:2 row_mask:0xf bank_mask:0xf
	s_nop 1
	v_mov_b32_dpp v14, v6 row_ror:2 row_mask:0xf bank_mask:0xf
	s_nop 1
	v_mov_b32_dpp v21, v7 row_ror:2 row_mask:0xf bank_mask:0xf
	s_waitcnt lgkmcnt(3)
	v_add_f32_e32 v4, v4, v8
	s_waitcnt lgkmcnt(2)
	v_add_f32_e32 v5, v5, v9
	s_waitcnt lgkmcnt(1)
	v_add_f32_e32 v6, v6, v14
	s_waitcnt lgkmcnt(0)
	v_add_f32_e32 v7, v7, v21
	s_nop 1
	v_mov_b32_dpp v8, v4 row_ror:1 row_mask:0xf bank_mask:0xf
	s_nop 1
	v_mov_b32_dpp v9, v5 row_ror:1 row_mask:0xf bank_mask:0xf
	s_nop 1
	v_mov_b32_dpp v14, v6 row_ror:1 row_mask:0xf bank_mask:0xf
	s_nop 1
	v_mov_b32_dpp v21, v7 row_ror:1 row_mask:0xf bank_mask:0xf
	s_waitcnt lgkmcnt(3)
	v_add_f32_e32 v4, v4, v8
	s_waitcnt lgkmcnt(2)
	v_add_f32_e32 v5, v5, v9
	s_waitcnt lgkmcnt(1)
	v_add_f32_e32 v6, v6, v14
	s_waitcnt lgkmcnt(0)
	v_add_f32_e32 v7, v7, v21
	v_fmamk_f32 v4, v4, 0x3a800000, v200
	v_mul_f32_e32 v8, 0x4b800000, v4
	v_cmp_gt_f32_e32 vcc, 0x800000, v4
	s_nop 1
	v_cndmask_b32_e32 v4, v4, v8, vcc
	v_rsq_f32_e32 v4, v4
	s_nop 0
	v_mul_f32_e32 v8, 0x45800000, v4
	v_cndmask_b32_e32 v4, v4, v8, vcc
	v_fmamk_f32 v5, v5, 0x3a800000, v200
	v_mul_f32_e32 v9, 0x4b800000, v5
	v_cmp_gt_f32_e32 vcc, 0x800000, v5
	s_nop 1
	v_cndmask_b32_e32 v5, v5, v9, vcc
	v_rsq_f32_e32 v5, v5
	s_nop 0
	v_mul_f32_e32 v9, 0x45800000, v5
	v_cndmask_b32_e32 v5, v5, v9, vcc
	v_fmamk_f32 v6, v6, 0x3a800000, v200
	v_mul_f32_e32 v14, 0x4b800000, v6
	v_cmp_gt_f32_e32 vcc, 0x800000, v6
	s_nop 1
	v_cndmask_b32_e32 v6, v6, v14, vcc
	v_rsq_f32_e32 v6, v6
	s_nop 0
	v_mul_f32_e32 v14, 0x45800000, v6
	v_cndmask_b32_e32 v6, v6, v14, vcc
	v_fmamk_f32 v7, v7, 0x3a800000, v200
	v_mul_f32_e32 v21, 0x4b800000, v7
	v_cmp_gt_f32_e32 vcc, 0x800000, v7
	s_nop 1
	v_cndmask_b32_e32 v7, v7, v21, vcc
	v_rsq_f32_e32 v7, v7
	s_nop 0
	v_mul_f32_e32 v21, 0x45800000, v7
	v_cndmask_b32_e32 v7, v7, v21, vcc
	v_mul_f32_e32 v96, v96, v4
	v_mul_f32_e32 v97, v97, v4
	v_mul_f32_e32 v98, v98, v4
	v_mul_f32_e32 v99, v99, v4
	v_mul_f32_e32 v96, v0, v96
	v_mul_f32_e32 v97, v1, v97
	v_mul_f32_e32 v98, v2, v98
	v_mul_f32_e32 v99, v3, v99
	v_fma_f32 v96, v24, v96, v52
	v_fma_f32 v97, v25, v97, v53
	v_fma_f32 v98, v26, v98, v54
	v_fma_f32 v99, v27, v99, v55
	v_cvt_pk_bf16_f32 v96, v96, v97
	v_cvt_pk_bf16_f32 v97, v98, v99
	global_store_dwordx2 v[12:13], v[96:97], off offset:-1024
	v_mul_f32_e32 v100, v100, v4
	v_mul_f32_e32 v101, v101, v4
	v_mul_f32_e32 v102, v102, v4
	v_mul_f32_e32 v103, v103, v4
	v_mul_f32_e32 v100, v40, v100
	v_mul_f32_e32 v101, v41, v101
	v_mul_f32_e32 v102, v42, v102
	v_mul_f32_e32 v103, v43, v103
	v_fma_f32 v100, v28, v100, v56
	v_fma_f32 v101, v29, v101, v57
	v_fma_f32 v102, v30, v102, v58
	v_fma_f32 v103, v31, v103, v59
	v_cvt_pk_bf16_f32 v100, v100, v101
	v_cvt_pk_bf16_f32 v101, v102, v103
	global_store_dwordx2 v[12:13], v[100:101], off offset:-512
	v_mul_f32_e32 v104, v104, v4
	v_mul_f32_e32 v105, v105, v4
	v_mul_f32_e32 v106, v106, v4
	v_mul_f32_e32 v107, v107, v4
	v_mul_f32_e32 v104, v44, v104
	v_mul_f32_e32 v105, v45, v105
	v_mul_f32_e32 v106, v46, v106
	v_mul_f32_e32 v107, v47, v107
	v_fma_f32 v104, v32, v104, v60
	v_fma_f32 v105, v33, v105, v61
	v_fma_f32 v106, v34, v106, v62
	v_fma_f32 v107, v35, v107, v63
	v_cvt_pk_bf16_f32 v104, v104, v105
	v_cvt_pk_bf16_f32 v105, v106, v107
	global_store_dwordx2 v[12:13], v[104:105], off
	v_mul_f32_e32 v108, v108, v4
	v_mul_f32_e32 v109, v109, v4
	v_mul_f32_e32 v110, v110, v4
	v_mul_f32_e32 v111, v111, v4
	v_mul_f32_e32 v108, v48, v108
	v_mul_f32_e32 v109, v49, v109
	v_mul_f32_e32 v110, v50, v110
	v_mul_f32_e32 v111, v51, v111
	v_fma_f32 v108, v36, v108, v64
	v_fma_f32 v109, v37, v109, v65
	v_fma_f32 v110, v38, v110, v66
	v_fma_f32 v111, v39, v111, v67
	v_cvt_pk_bf16_f32 v108, v108, v109
	v_cvt_pk_bf16_f32 v109, v110, v111
	global_store_dwordx2 v[12:13], v[108:109], off offset:512
	v_lshl_add_u64 v[12:13], v[12:13], 0, s[40:41]
	v_mul_f32_e32 v112, v112, v5
	v_mul_f32_e32 v113, v113, v5
	v_mul_f32_e32 v114, v114, v5
	v_mul_f32_e32 v115, v115, v5
	v_mul_f32_e32 v112, v0, v112
	v_mul_f32_e32 v113, v1, v113
	v_mul_f32_e32 v114, v2, v114
	v_mul_f32_e32 v115, v3, v115
	v_fma_f32 v112, v24, v112, v52
	v_fma_f32 v113, v25, v113, v53
	v_fma_f32 v114, v26, v114, v54
	v_fma_f32 v115, v27, v115, v55
	v_cvt_pk_bf16_f32 v112, v112, v113
	v_cvt_pk_bf16_f32 v113, v114, v115
	global_store_dwordx2 v[12:13], v[112:113], off offset:-1024
	v_mul_f32_e32 v116, v116, v5
	v_mul_f32_e32 v117, v117, v5
	v_mul_f32_e32 v118, v118, v5
	v_mul_f32_e32 v119, v119, v5
	v_mul_f32_e32 v116, v40, v116
	v_mul_f32_e32 v117, v41, v117
	v_mul_f32_e32 v118, v42, v118
	v_mul_f32_e32 v119, v43, v119
	v_fma_f32 v116, v28, v116, v56
	v_fma_f32 v117, v29, v117, v57
	v_fma_f32 v118, v30, v118, v58
	v_fma_f32 v119, v31, v119, v59
	v_cvt_pk_bf16_f32 v116, v116, v117
	v_cvt_pk_bf16_f32 v117, v118, v119
	global_store_dwordx2 v[12:13], v[116:117], off offset:-512
	v_mul_f32_e32 v120, v120, v5
	v_mul_f32_e32 v121, v121, v5
	v_mul_f32_e32 v122, v122, v5
	v_mul_f32_e32 v123, v123, v5
	v_mul_f32_e32 v120, v44, v120
	v_mul_f32_e32 v121, v45, v121
	v_mul_f32_e32 v122, v46, v122
	v_mul_f32_e32 v123, v47, v123
	v_fma_f32 v120, v32, v120, v60
	v_fma_f32 v121, v33, v121, v61
	v_fma_f32 v122, v34, v122, v62
	v_fma_f32 v123, v35, v123, v63
	v_cvt_pk_bf16_f32 v120, v120, v121
	v_cvt_pk_bf16_f32 v121, v122, v123
	global_store_dwordx2 v[12:13], v[120:121], off
	v_mul_f32_e32 v124, v124, v5
	v_mul_f32_e32 v125, v125, v5
	v_mul_f32_e32 v126, v126, v5
	v_mul_f32_e32 v127, v127, v5
	v_mul_f32_e32 v124, v48, v124
	v_mul_f32_e32 v125, v49, v125
	v_mul_f32_e32 v126, v50, v126
	v_mul_f32_e32 v127, v51, v127
	v_fma_f32 v124, v36, v124, v64
	v_fma_f32 v125, v37, v125, v65
	v_fma_f32 v126, v38, v126, v66
	v_fma_f32 v127, v39, v127, v67
	v_cvt_pk_bf16_f32 v124, v124, v125
	v_cvt_pk_bf16_f32 v125, v126, v127
	global_store_dwordx2 v[12:13], v[124:125], off offset:512
	v_lshl_add_u64 v[12:13], v[12:13], 0, s[40:41]
	v_mul_f32_e32 v128, v128, v6
	v_mul_f32_e32 v129, v129, v6
	v_mul_f32_e32 v130, v130, v6
	v_mul_f32_e32 v131, v131, v6
	v_mul_f32_e32 v128, v0, v128
	v_mul_f32_e32 v129, v1, v129
	v_mul_f32_e32 v130, v2, v130
	v_mul_f32_e32 v131, v3, v131
	v_fma_f32 v128, v24, v128, v52
	v_fma_f32 v129, v25, v129, v53
	v_fma_f32 v130, v26, v130, v54
	v_fma_f32 v131, v27, v131, v55
	v_cvt_pk_bf16_f32 v128, v128, v129
	v_cvt_pk_bf16_f32 v129, v130, v131
	global_store_dwordx2 v[12:13], v[128:129], off offset:-1024
	v_mul_f32_e32 v132, v132, v6
	v_mul_f32_e32 v133, v133, v6
	v_mul_f32_e32 v134, v134, v6
	v_mul_f32_e32 v135, v135, v6
	v_mul_f32_e32 v132, v40, v132
	v_mul_f32_e32 v133, v41, v133
	v_mul_f32_e32 v134, v42, v134
	v_mul_f32_e32 v135, v43, v135
	v_fma_f32 v132, v28, v132, v56
	v_fma_f32 v133, v29, v133, v57
	v_fma_f32 v134, v30, v134, v58
	v_fma_f32 v135, v31, v135, v59
	v_cvt_pk_bf16_f32 v132, v132, v133
	v_cvt_pk_bf16_f32 v133, v134, v135
	global_store_dwordx2 v[12:13], v[132:133], off offset:-512
	v_mul_f32_e32 v136, v136, v6
	v_mul_f32_e32 v137, v137, v6
	v_mul_f32_e32 v138, v138, v6
	v_mul_f32_e32 v139, v139, v6
	v_mul_f32_e32 v136, v44, v136
	v_mul_f32_e32 v137, v45, v137
	v_mul_f32_e32 v138, v46, v138
	v_mul_f32_e32 v139, v47, v139
	v_fma_f32 v136, v32, v136, v60
	v_fma_f32 v137, v33, v137, v61
	v_fma_f32 v138, v34, v138, v62
	v_fma_f32 v139, v35, v139, v63
	v_cvt_pk_bf16_f32 v136, v136, v137
	v_cvt_pk_bf16_f32 v137, v138, v139
	global_store_dwordx2 v[12:13], v[136:137], off
	v_mul_f32_e32 v140, v140, v6
	v_mul_f32_e32 v141, v141, v6
	v_mul_f32_e32 v142, v142, v6
	v_mul_f32_e32 v143, v143, v6
	v_mul_f32_e32 v140, v48, v140
	v_mul_f32_e32 v141, v49, v141
	v_mul_f32_e32 v142, v50, v142
	v_mul_f32_e32 v143, v51, v143
	v_fma_f32 v140, v36, v140, v64
	v_fma_f32 v141, v37, v141, v65
	v_fma_f32 v142, v38, v142, v66
	v_fma_f32 v143, v39, v143, v67
	v_cvt_pk_bf16_f32 v140, v140, v141
	v_cvt_pk_bf16_f32 v141, v142, v143
	global_store_dwordx2 v[12:13], v[140:141], off offset:512
	v_lshl_add_u64 v[12:13], v[12:13], 0, s[40:41]
	v_mul_f32_e32 v160, v160, v7
	v_mul_f32_e32 v161, v161, v7
	v_mul_f32_e32 v162, v162, v7
	v_mul_f32_e32 v163, v163, v7
	v_mul_f32_e32 v160, v0, v160
	v_mul_f32_e32 v161, v1, v161
	v_mul_f32_e32 v162, v2, v162
	v_mul_f32_e32 v163, v3, v163
	v_fma_f32 v160, v24, v160, v52
	v_fma_f32 v161, v25, v161, v53
	v_fma_f32 v162, v26, v162, v54
	v_fma_f32 v163, v27, v163, v55
	v_cvt_pk_bf16_f32 v160, v160, v161
	v_cvt_pk_bf16_f32 v161, v162, v163
	global_store_dwordx2 v[12:13], v[160:161], off offset:-1024
	v_mul_f32_e32 v164, v164, v7
	v_mul_f32_e32 v165, v165, v7
	v_mul_f32_e32 v166, v166, v7
	v_mul_f32_e32 v167, v167, v7
	v_mul_f32_e32 v164, v40, v164
	v_mul_f32_e32 v165, v41, v165
	v_mul_f32_e32 v166, v42, v166
	v_mul_f32_e32 v167, v43, v167
	v_fma_f32 v164, v28, v164, v56
	v_fma_f32 v165, v29, v165, v57
	v_fma_f32 v166, v30, v166, v58
	v_fma_f32 v167, v31, v167, v59
	v_cvt_pk_bf16_f32 v164, v164, v165
	v_cvt_pk_bf16_f32 v165, v166, v167
	global_store_dwordx2 v[12:13], v[164:165], off offset:-512
	v_mul_f32_e32 v168, v168, v7
	v_mul_f32_e32 v169, v169, v7
	v_mul_f32_e32 v170, v170, v7
	v_mul_f32_e32 v171, v171, v7
	v_mul_f32_e32 v168, v44, v168
	v_mul_f32_e32 v169, v45, v169
	v_mul_f32_e32 v170, v46, v170
	v_mul_f32_e32 v171, v47, v171
	v_fma_f32 v168, v32, v168, v60
	v_fma_f32 v169, v33, v169, v61
	v_fma_f32 v170, v34, v170, v62
	v_fma_f32 v171, v35, v171, v63
	v_cvt_pk_bf16_f32 v168, v168, v169
	v_cvt_pk_bf16_f32 v169, v170, v171
	global_store_dwordx2 v[12:13], v[168:169], off
	v_mul_f32_e32 v172, v172, v7
	v_mul_f32_e32 v173, v173, v7
	v_mul_f32_e32 v174, v174, v7
	v_mul_f32_e32 v175, v175, v7
	v_mul_f32_e32 v172, v48, v172
	v_mul_f32_e32 v173, v49, v173
	v_mul_f32_e32 v174, v50, v174
	v_mul_f32_e32 v175, v51, v175
	v_fma_f32 v172, v36, v172, v64
	v_fma_f32 v173, v37, v173, v65
	v_fma_f32 v174, v38, v174, v66
	v_fma_f32 v175, v39, v175, v67
	v_cvt_pk_bf16_f32 v172, v172, v173
	v_cvt_pk_bf16_f32 v173, v174, v175
	global_store_dwordx2 v[12:13], v[172:173], off offset:512
	v_lshl_add_u64 v[12:13], v[12:13], 0, s[40:41]
	s_waitcnt vmcnt(16)
	v_mul_f32_e32 v4, v176, v176
	v_fmac_f32_e32 v4, v177, v177
	v_fmac_f32_e32 v4, v178, v178
	v_fmac_f32_e32 v4, v179, v179
	v_fmac_f32_e32 v4, v180, v180
	v_fmac_f32_e32 v4, v181, v181
	v_fmac_f32_e32 v4, v182, v182
	v_fmac_f32_e32 v4, v183, v183
	v_fmac_f32_e32 v4, v184, v184
	v_fmac_f32_e32 v4, v185, v185
	v_fmac_f32_e32 v4, v186, v186
	v_fmac_f32_e32 v4, v187, v187
	v_fmac_f32_e32 v4, v188, v188
	v_fmac_f32_e32 v4, v189, v189
	v_fmac_f32_e32 v4, v190, v190
	v_fmac_f32_e32 v4, v191, v191
	v_mul_f32_e32 v5, v214, v214
	v_fmac_f32_e32 v5, v215, v215
	v_fmac_f32_e32 v5, v216, v216
	v_fmac_f32_e32 v5, v217, v217
	v_fmac_f32_e32 v5, v218, v218
	v_fmac_f32_e32 v5, v219, v219
	v_fmac_f32_e32 v5, v220, v220
	v_fmac_f32_e32 v5, v221, v221
	v_fmac_f32_e32 v5, v222, v222
	v_fmac_f32_e32 v5, v223, v223
	v_fmac_f32_e32 v5, v224, v224
	v_fmac_f32_e32 v5, v225, v225
	v_fmac_f32_e32 v5, v226, v226
	v_fmac_f32_e32 v5, v227, v227
	v_fmac_f32_e32 v5, v228, v228
	v_fmac_f32_e32 v5, v229, v229
	v_mul_f32_e32 v6, v76, v76
	v_fmac_f32_e32 v6, v77, v77
	v_fmac_f32_e32 v6, v78, v78
	v_fmac_f32_e32 v6, v79, v79
	v_fmac_f32_e32 v6, v80, v80
	v_fmac_f32_e32 v6, v81, v81
	v_fmac_f32_e32 v6, v82, v82
	v_fmac_f32_e32 v6, v83, v83
	v_fmac_f32_e32 v6, v84, v84
	v_fmac_f32_e32 v6, v85, v85
	v_fmac_f32_e32 v6, v86, v86
	v_fmac_f32_e32 v6, v87, v87
	v_fmac_f32_e32 v6, v88, v88
	v_fmac_f32_e32 v6, v89, v89
	v_fmac_f32_e32 v6, v90, v90
	v_fmac_f32_e32 v6, v91, v91
	v_mul_f32_e32 v7, v144, v144
	v_fmac_f32_e32 v7, v145, v145
	v_fmac_f32_e32 v7, v146, v146
	v_fmac_f32_e32 v7, v147, v147
	v_fmac_f32_e32 v7, v148, v148
	v_fmac_f32_e32 v7, v149, v149
	v_fmac_f32_e32 v7, v150, v150
	v_fmac_f32_e32 v7, v151, v151
	v_fmac_f32_e32 v7, v152, v152
	v_fmac_f32_e32 v7, v153, v153
	v_fmac_f32_e32 v7, v154, v154
	v_fmac_f32_e32 v7, v155, v155
	v_fmac_f32_e32 v7, v230, v230
	v_fmac_f32_e32 v7, v231, v231
	v_fmac_f32_e32 v7, v232, v232
	v_fmac_f32_e32 v7, v233, v233
	v_mov_b32_e32 v8, v4
	s_nop 1
	v_permlane32_swap_b32_e32 v8, v4
	v_mov_b32_e32 v9, v5
	s_nop 1
	v_permlane32_swap_b32_e32 v9, v5
	v_mov_b32_e32 v14, v6
	s_nop 1
	v_permlane32_swap_b32_e32 v14, v6
	v_mov_b32_e32 v21, v7
	s_nop 1
	v_permlane32_swap_b32_e32 v21, v7
	s_waitcnt lgkmcnt(3)
	v_add_f32_e32 v4, v4, v8
	s_waitcnt lgkmcnt(2)
	v_add_f32_e32 v5, v5, v9
	s_waitcnt lgkmcnt(1)
	v_add_f32_e32 v6, v6, v14
	s_waitcnt lgkmcnt(0)
	v_add_f32_e32 v7, v7, v21
	v_mov_b32_e32 v8, v4
	s_nop 1
	v_permlane16_swap_b32_e32 v8, v4
	v_mov_b32_e32 v9, v5
	s_nop 1
	v_permlane16_swap_b32_e32 v9, v5
	v_mov_b32_e32 v14, v6
	s_nop 1
	v_permlane16_swap_b32_e32 v14, v6
	v_mov_b32_e32 v21, v7
	s_nop 1
	v_permlane16_swap_b32_e32 v21, v7
	s_waitcnt lgkmcnt(3)
	v_add_f32_e32 v4, v4, v8
	s_waitcnt lgkmcnt(2)
	v_add_f32_e32 v5, v5, v9
	s_waitcnt lgkmcnt(1)
	v_add_f32_e32 v6, v6, v14
	s_waitcnt lgkmcnt(0)
	v_add_f32_e32 v7, v7, v21
	s_nop 1
	v_mov_b32_dpp v8, v4 row_ror:8 row_mask:0xf bank_mask:0xf
	s_nop 1
	v_mov_b32_dpp v9, v5 row_ror:8 row_mask:0xf bank_mask:0xf
	s_nop 1
	v_mov_b32_dpp v14, v6 row_ror:8 row_mask:0xf bank_mask:0xf
	s_nop 1
	v_mov_b32_dpp v21, v7 row_ror:8 row_mask:0xf bank_mask:0xf
	s_waitcnt lgkmcnt(3)
	v_add_f32_e32 v4, v4, v8
	s_waitcnt lgkmcnt(2)
	v_add_f32_e32 v5, v5, v9
	s_waitcnt lgkmcnt(1)
	v_add_f32_e32 v6, v6, v14
	s_waitcnt lgkmcnt(0)
	v_add_f32_e32 v7, v7, v21
	s_nop 1
	v_mov_b32_dpp v8, v4 row_ror:4 row_mask:0xf bank_mask:0xf
	s_nop 1
	v_mov_b32_dpp v9, v5 row_ror:4 row_mask:0xf bank_mask:0xf
	s_nop 1
	v_mov_b32_dpp v14, v6 row_ror:4 row_mask:0xf bank_mask:0xf
	s_nop 1
	v_mov_b32_dpp v21, v7 row_ror:4 row_mask:0xf bank_mask:0xf
	s_waitcnt lgkmcnt(3)
	v_add_f32_e32 v4, v4, v8
	s_waitcnt lgkmcnt(2)
	v_add_f32_e32 v5, v5, v9
	s_waitcnt lgkmcnt(1)
	v_add_f32_e32 v6, v6, v14
	s_waitcnt lgkmcnt(0)
	v_add_f32_e32 v7, v7, v21
	s_nop 1
	v_mov_b32_dpp v8, v4 row_ror:2 row_mask:0xf bank_mask:0xf
	s_nop 1
	v_mov_b32_dpp v9, v5 row_ror:2 row_mask:0xf bank_mask:0xf
	s_nop 1
	v_mov_b32_dpp v14, v6 row_ror:2 row_mask:0xf bank_mask:0xf
	s_nop 1
	v_mov_b32_dpp v21, v7 row_ror:2 row_mask:0xf bank_mask:0xf
	s_waitcnt lgkmcnt(3)
	v_add_f32_e32 v4, v4, v8
	s_waitcnt lgkmcnt(2)
	v_add_f32_e32 v5, v5, v9
	s_waitcnt lgkmcnt(1)
	v_add_f32_e32 v6, v6, v14
	s_waitcnt lgkmcnt(0)
	v_add_f32_e32 v7, v7, v21
	s_nop 1
	v_mov_b32_dpp v8, v4 row_ror:1 row_mask:0xf bank_mask:0xf
	s_nop 1
	v_mov_b32_dpp v9, v5 row_ror:1 row_mask:0xf bank_mask:0xf
	s_nop 1
	v_mov_b32_dpp v14, v6 row_ror:1 row_mask:0xf bank_mask:0xf
	s_nop 1
	v_mov_b32_dpp v21, v7 row_ror:1 row_mask:0xf bank_mask:0xf
	s_waitcnt lgkmcnt(3)
	v_add_f32_e32 v4, v4, v8
	s_waitcnt lgkmcnt(2)
	v_add_f32_e32 v5, v5, v9
	s_waitcnt lgkmcnt(1)
	v_add_f32_e32 v6, v6, v14
	s_waitcnt lgkmcnt(0)
	v_add_f32_e32 v7, v7, v21
	v_fmamk_f32 v4, v4, 0x3a800000, v200
	v_mul_f32_e32 v8, 0x4b800000, v4
	v_cmp_gt_f32_e32 vcc, 0x800000, v4
	s_nop 1
	v_cndmask_b32_e32 v4, v4, v8, vcc
	v_rsq_f32_e32 v4, v4
	s_nop 0
	v_mul_f32_e32 v8, 0x45800000, v4
	v_cndmask_b32_e32 v4, v4, v8, vcc
	v_fmamk_f32 v5, v5, 0x3a800000, v200
	v_mul_f32_e32 v9, 0x4b800000, v5
	v_cmp_gt_f32_e32 vcc, 0x800000, v5
	s_nop 1
	v_cndmask_b32_e32 v5, v5, v9, vcc
	v_rsq_f32_e32 v5, v5
	s_nop 0
	v_mul_f32_e32 v9, 0x45800000, v5
	v_cndmask_b32_e32 v5, v5, v9, vcc
	v_fmamk_f32 v6, v6, 0x3a800000, v200
	v_mul_f32_e32 v14, 0x4b800000, v6
	v_cmp_gt_f32_e32 vcc, 0x800000, v6
	s_nop 1
	v_cndmask_b32_e32 v6, v6, v14, vcc
	v_rsq_f32_e32 v6, v6
	s_nop 0
	v_mul_f32_e32 v14, 0x45800000, v6
	v_cndmask_b32_e32 v6, v6, v14, vcc
	v_fmamk_f32 v7, v7, 0x3a800000, v200
	v_mul_f32_e32 v21, 0x4b800000, v7
	v_cmp_gt_f32_e32 vcc, 0x800000, v7
	s_nop 1
	v_cndmask_b32_e32 v7, v7, v21, vcc
	v_rsq_f32_e32 v7, v7
	s_nop 0
	v_mul_f32_e32 v21, 0x45800000, v7
	v_cndmask_b32_e32 v7, v7, v21, vcc
	v_mul_f32_e32 v176, v176, v4
	v_mul_f32_e32 v177, v177, v4
	v_mul_f32_e32 v178, v178, v4
	v_mul_f32_e32 v179, v179, v4
	v_mul_f32_e32 v176, v0, v176
	v_mul_f32_e32 v177, v1, v177
	v_mul_f32_e32 v178, v2, v178
	v_mul_f32_e32 v179, v3, v179
	v_fma_f32 v176, v24, v176, v52
	v_fma_f32 v177, v25, v177, v53
	v_fma_f32 v178, v26, v178, v54
	v_fma_f32 v179, v27, v179, v55
	v_cvt_pk_bf16_f32 v176, v176, v177
	v_cvt_pk_bf16_f32 v177, v178, v179
	global_store_dwordx2 v[12:13], v[176:177], off offset:-1024
	v_mul_f32_e32 v180, v180, v4
	v_mul_f32_e32 v181, v181, v4
	v_mul_f32_e32 v182, v182, v4
	v_mul_f32_e32 v183, v183, v4
	v_mul_f32_e32 v180, v40, v180
	v_mul_f32_e32 v181, v41, v181
	v_mul_f32_e32 v182, v42, v182
	v_mul_f32_e32 v183, v43, v183
	v_fma_f32 v180, v28, v180, v56
	v_fma_f32 v181, v29, v181, v57
	v_fma_f32 v182, v30, v182, v58
	v_fma_f32 v183, v31, v183, v59
	v_cvt_pk_bf16_f32 v180, v180, v181
	v_cvt_pk_bf16_f32 v181, v182, v183
	global_store_dwordx2 v[12:13], v[180:181], off offset:-512
	v_mul_f32_e32 v184, v184, v4
	v_mul_f32_e32 v185, v185, v4
	v_mul_f32_e32 v186, v186, v4
	v_mul_f32_e32 v187, v187, v4
	v_mul_f32_e32 v184, v44, v184
	v_mul_f32_e32 v185, v45, v185
	v_mul_f32_e32 v186, v46, v186
	v_mul_f32_e32 v187, v47, v187
	v_fma_f32 v184, v32, v184, v60
	v_fma_f32 v185, v33, v185, v61
	v_fma_f32 v186, v34, v186, v62
	v_fma_f32 v187, v35, v187, v63
	v_cvt_pk_bf16_f32 v184, v184, v185
	v_cvt_pk_bf16_f32 v185, v186, v187
	global_store_dwordx2 v[12:13], v[184:185], off
	v_mul_f32_e32 v188, v188, v4
	v_mul_f32_e32 v189, v189, v4
	v_mul_f32_e32 v190, v190, v4
	v_mul_f32_e32 v191, v191, v4
	v_mul_f32_e32 v188, v48, v188
	v_mul_f32_e32 v189, v49, v189
	v_mul_f32_e32 v190, v50, v190
	v_mul_f32_e32 v191, v51, v191
	v_fma_f32 v188, v36, v188, v64
	v_fma_f32 v189, v37, v189, v65
	v_fma_f32 v190, v38, v190, v66
	v_fma_f32 v191, v39, v191, v67
	v_cvt_pk_bf16_f32 v188, v188, v189
	v_cvt_pk_bf16_f32 v189, v190, v191
	global_store_dwordx2 v[12:13], v[188:189], off offset:512
	v_lshl_add_u64 v[12:13], v[12:13], 0, s[40:41]
	v_mul_f32_e32 v214, v214, v5
	v_mul_f32_e32 v215, v215, v5
	v_mul_f32_e32 v216, v216, v5
	v_mul_f32_e32 v217, v217, v5
	v_mul_f32_e32 v214, v0, v214
	v_mul_f32_e32 v215, v1, v215
	v_mul_f32_e32 v216, v2, v216
	v_mul_f32_e32 v217, v3, v217
	v_fma_f32 v214, v24, v214, v52
	v_fma_f32 v215, v25, v215, v53
	v_fma_f32 v216, v26, v216, v54
	v_fma_f32 v217, v27, v217, v55
	v_cvt_pk_bf16_f32 v214, v214, v215
	v_cvt_pk_bf16_f32 v215, v216, v217
	global_store_dwordx2 v[12:13], v[214:215], off offset:-1024
	v_mul_f32_e32 v218, v218, v5
	v_mul_f32_e32 v219, v219, v5
	v_mul_f32_e32 v220, v220, v5
	v_mul_f32_e32 v221, v221, v5
	v_mul_f32_e32 v218, v40, v218
	v_mul_f32_e32 v219, v41, v219
	v_mul_f32_e32 v220, v42, v220
	v_mul_f32_e32 v221, v43, v221
	v_fma_f32 v218, v28, v218, v56
	v_fma_f32 v219, v29, v219, v57
	v_fma_f32 v220, v30, v220, v58
	v_fma_f32 v221, v31, v221, v59
	v_cvt_pk_bf16_f32 v218, v218, v219
	v_cvt_pk_bf16_f32 v219, v220, v221
	global_store_dwordx2 v[12:13], v[218:219], off offset:-512
	v_mul_f32_e32 v222, v222, v5
	v_mul_f32_e32 v223, v223, v5
	v_mul_f32_e32 v224, v224, v5
	v_mul_f32_e32 v225, v225, v5
	v_mul_f32_e32 v222, v44, v222
	v_mul_f32_e32 v223, v45, v223
	v_mul_f32_e32 v224, v46, v224
	v_mul_f32_e32 v225, v47, v225
	v_fma_f32 v222, v32, v222, v60
	v_fma_f32 v223, v33, v223, v61
	v_fma_f32 v224, v34, v224, v62
	v_fma_f32 v225, v35, v225, v63
	v_cvt_pk_bf16_f32 v222, v222, v223
	v_cvt_pk_bf16_f32 v223, v224, v225
	global_store_dwordx2 v[12:13], v[222:223], off
	v_mul_f32_e32 v226, v226, v5
	v_mul_f32_e32 v227, v227, v5
	v_mul_f32_e32 v228, v228, v5
	v_mul_f32_e32 v229, v229, v5
	v_mul_f32_e32 v226, v48, v226
	v_mul_f32_e32 v227, v49, v227
	v_mul_f32_e32 v228, v50, v228
	v_mul_f32_e32 v229, v51, v229
	v_fma_f32 v226, v36, v226, v64
	v_fma_f32 v227, v37, v227, v65
	v_fma_f32 v228, v38, v228, v66
	v_fma_f32 v229, v39, v229, v67
	v_cvt_pk_bf16_f32 v226, v226, v227
	v_cvt_pk_bf16_f32 v227, v228, v229
	global_store_dwordx2 v[12:13], v[226:227], off offset:512
	v_lshl_add_u64 v[12:13], v[12:13], 0, s[40:41]
	v_mul_f32_e32 v76, v76, v6
	v_mul_f32_e32 v77, v77, v6
	v_mul_f32_e32 v78, v78, v6
	v_mul_f32_e32 v79, v79, v6
	v_mul_f32_e32 v76, v0, v76
	v_mul_f32_e32 v77, v1, v77
	v_mul_f32_e32 v78, v2, v78
	v_mul_f32_e32 v79, v3, v79
	v_fma_f32 v76, v24, v76, v52
	v_fma_f32 v77, v25, v77, v53
	v_fma_f32 v78, v26, v78, v54
	v_fma_f32 v79, v27, v79, v55
	v_cvt_pk_bf16_f32 v76, v76, v77
	v_cvt_pk_bf16_f32 v77, v78, v79
	global_store_dwordx2 v[12:13], v[76:77], off offset:-1024
	v_mul_f32_e32 v80, v80, v6
	v_mul_f32_e32 v81, v81, v6
	v_mul_f32_e32 v82, v82, v6
	v_mul_f32_e32 v83, v83, v6
	v_mul_f32_e32 v80, v40, v80
	v_mul_f32_e32 v81, v41, v81
	v_mul_f32_e32 v82, v42, v82
	v_mul_f32_e32 v83, v43, v83
	v_fma_f32 v80, v28, v80, v56
	v_fma_f32 v81, v29, v81, v57
	v_fma_f32 v82, v30, v82, v58
	v_fma_f32 v83, v31, v83, v59
	v_cvt_pk_bf16_f32 v80, v80, v81
	v_cvt_pk_bf16_f32 v81, v82, v83
	global_store_dwordx2 v[12:13], v[80:81], off offset:-512
	v_mul_f32_e32 v84, v84, v6
	v_mul_f32_e32 v85, v85, v6
	v_mul_f32_e32 v86, v86, v6
	v_mul_f32_e32 v87, v87, v6
	v_mul_f32_e32 v84, v44, v84
	v_mul_f32_e32 v85, v45, v85
	v_mul_f32_e32 v86, v46, v86
	v_mul_f32_e32 v87, v47, v87
	v_fma_f32 v84, v32, v84, v60
	v_fma_f32 v85, v33, v85, v61
	v_fma_f32 v86, v34, v86, v62
	v_fma_f32 v87, v35, v87, v63
	v_cvt_pk_bf16_f32 v84, v84, v85
	v_cvt_pk_bf16_f32 v85, v86, v87
	global_store_dwordx2 v[12:13], v[84:85], off
	v_mul_f32_e32 v88, v88, v6
	v_mul_f32_e32 v89, v89, v6
	v_mul_f32_e32 v90, v90, v6
	v_mul_f32_e32 v91, v91, v6
	v_mul_f32_e32 v88, v48, v88
	v_mul_f32_e32 v89, v49, v89
	v_mul_f32_e32 v90, v50, v90
	v_mul_f32_e32 v91, v51, v91
	v_fma_f32 v88, v36, v88, v64
	v_fma_f32 v89, v37, v89, v65
	v_fma_f32 v90, v38, v90, v66
	v_fma_f32 v91, v39, v91, v67
	v_cvt_pk_bf16_f32 v88, v88, v89
	v_cvt_pk_bf16_f32 v89, v90, v91
	global_store_dwordx2 v[12:13], v[88:89], off offset:512
	v_lshl_add_u64 v[12:13], v[12:13], 0, s[40:41]
	v_mul_f32_e32 v144, v144, v7
	v_mul_f32_e32 v145, v145, v7
	v_mul_f32_e32 v146, v146, v7
	v_mul_f32_e32 v147, v147, v7
	v_mul_f32_e32 v144, v0, v144
	v_mul_f32_e32 v145, v1, v145
	v_mul_f32_e32 v146, v2, v146
	v_mul_f32_e32 v147, v3, v147
	v_fma_f32 v144, v24, v144, v52
	v_fma_f32 v145, v25, v145, v53
	v_fma_f32 v146, v26, v146, v54
	v_fma_f32 v147, v27, v147, v55
	v_cvt_pk_bf16_f32 v144, v144, v145
	v_cvt_pk_bf16_f32 v145, v146, v147
	global_store_dwordx2 v[12:13], v[144:145], off offset:-1024
	v_mul_f32_e32 v148, v148, v7
	v_mul_f32_e32 v149, v149, v7
	v_mul_f32_e32 v150, v150, v7
	v_mul_f32_e32 v151, v151, v7
	v_mul_f32_e32 v148, v40, v148
	v_mul_f32_e32 v149, v41, v149
	v_mul_f32_e32 v150, v42, v150
	v_mul_f32_e32 v151, v43, v151
	v_fma_f32 v148, v28, v148, v56
	v_fma_f32 v149, v29, v149, v57
	v_fma_f32 v150, v30, v150, v58
	v_fma_f32 v151, v31, v151, v59
	v_cvt_pk_bf16_f32 v148, v148, v149
	v_cvt_pk_bf16_f32 v149, v150, v151
	global_store_dwordx2 v[12:13], v[148:149], off offset:-512
	v_mul_f32_e32 v152, v152, v7
	v_mul_f32_e32 v153, v153, v7
	v_mul_f32_e32 v154, v154, v7
	v_mul_f32_e32 v155, v155, v7
	v_mul_f32_e32 v152, v44, v152
	v_mul_f32_e32 v153, v45, v153
	v_mul_f32_e32 v154, v46, v154
	v_mul_f32_e32 v155, v47, v155
	v_fma_f32 v152, v32, v152, v60
	v_fma_f32 v153, v33, v153, v61
	v_fma_f32 v154, v34, v154, v62
	v_fma_f32 v155, v35, v155, v63
	v_cvt_pk_bf16_f32 v152, v152, v153
	v_cvt_pk_bf16_f32 v153, v154, v155
	global_store_dwordx2 v[12:13], v[152:153], off
	v_mul_f32_e32 v230, v230, v7
	v_mul_f32_e32 v231, v231, v7
	v_mul_f32_e32 v232, v232, v7
	v_mul_f32_e32 v233, v233, v7
	v_mul_f32_e32 v230, v48, v230
	v_mul_f32_e32 v231, v49, v231
	v_mul_f32_e32 v232, v50, v232
	v_mul_f32_e32 v233, v51, v233
	v_fma_f32 v230, v36, v230, v64
	v_fma_f32 v231, v37, v231, v65
	v_fma_f32 v232, v38, v232, v66
	v_fma_f32 v233, v39, v233, v67
	v_cvt_pk_bf16_f32 v230, v230, v231
	v_cvt_pk_bf16_f32 v231, v232, v233
	global_store_dwordx2 v[12:13], v[230:231], off offset:512
	v_lshl_add_u64 v[12:13], v[12:13], 0, s[40:41]
	s_branch .LBB0_434
.LBB0_433:
	global_load_dwordx4 v[22:25], v[10:11], off offset:-2048
	global_load_dwordx4 v[26:29], v[10:11], off offset:-1024
	global_load_dwordx4 v[30:33], v[10:11], off
	global_load_dwordx4 v[34:37], v[10:11], off offset:1024
	v_ashrrev_i32_e32 v21, 11, v14
	v_mul_hi_i32_i24_e32 v39, 0x2400, v21
	v_mul_i32_i24_e32 v38, 0x2400, v21
	v_lshlrev_b64 v[38:39], 2, v[38:39]
	v_lshl_add_u64 v[46:47], v[6:7], 0, v[38:39]
	v_lshl_add_u64 v[48:49], v[8:9], 0, v[38:39]
	global_load_dwordx4 v[38:41], v[46:47], off
	global_load_dwordx4 v[42:45], v[48:49], off
	v_add_u32_e32 v14, s30, v14
	v_lshl_add_u64 v[10:11], v[10:11], 0, s[34:35]
	s_waitcnt vmcnt(5)
	v_mov_b32_e32 v52, v23
	s_waitcnt vmcnt(4)
	v_mov_b32_e32 v53, v27
	v_mov_b32_e32 v50, v22
	v_mov_b32_e32 v51, v26
	s_waitcnt vmcnt(3)
	v_mov_b32_e32 v60, v31
	s_waitcnt vmcnt(2)
	v_mov_b32_e32 v61, v35
	v_pk_mul_f32 v[52:53], v[52:53], v[52:53]
	v_mov_b32_e32 v54, v24
	v_mov_b32_e32 v55, v28
	v_mov_b32_e32 v58, v30
	v_mov_b32_e32 v59, v34
	v_pk_mul_f32 v[60:61], v[60:61], v[60:61]
	v_pk_fma_f32 v[50:51], v[50:51], v[50:51], v[52:53]
	v_mov_b32_e32 v56, v25
	v_mov_b32_e32 v57, v29
	v_mov_b32_e32 v62, v32
	v_mov_b32_e32 v63, v36
	v_pk_fma_f32 v[52:53], v[58:59], v[58:59], v[60:61]
	v_pk_fma_f32 v[50:51], v[54:55], v[54:55], v[50:51]
	v_mov_b32_e32 v64, v33
	v_mov_b32_e32 v65, v37
	v_pk_fma_f32 v[52:53], v[62:63], v[62:63], v[52:53]
	v_pk_fma_f32 v[50:51], v[56:57], v[56:57], v[50:51]
	v_pk_fma_f32 v[52:53], v[64:65], v[64:65], v[52:53]
	s_waitcnt vmcnt(1)
	v_add_f32_e32 v21, 1.0, v38
	v_add_f32_e32 v38, 1.0, v39
	v_add_f32_e32 v39, 1.0, v40
	v_add_f32_e32 v40, 1.0, v41
	v_add_f32_e32 v41, v50, v51
	v_add_f32_e32 v41, v41, v52
	v_add_f32_e32 v41, v41, v53
	v_mov_b32_e32 v50, v41
	s_nop 1
	v_permlane32_swap_b32_e32 v50, v41
	s_waitcnt lgkmcnt(0)
	v_add_f32_e32 v41, v41, v50
	v_mov_b32_e32 v50, v41
	s_nop 1
	v_permlane16_swap_b32_e32 v50, v41
	s_waitcnt lgkmcnt(0)
	v_add_f32_e32 v41, v41, v50
	s_nop 1
	v_mov_b32_dpp v50, v41 row_ror:8 row_mask:0xf bank_mask:0xf
	s_waitcnt lgkmcnt(0)
	v_add_f32_e32 v41, v41, v50
	s_nop 1
	v_mov_b32_dpp v50, v41 row_ror:4 row_mask:0xf bank_mask:0xf
	s_waitcnt lgkmcnt(0)
	v_add_f32_e32 v41, v41, v50
	s_nop 1
	v_mov_b32_dpp v50, v41 row_ror:2 row_mask:0xf bank_mask:0xf
	s_waitcnt lgkmcnt(0)
	v_add_f32_e32 v41, v41, v50
	s_nop 1
	v_mov_b32_dpp v50, v41 row_ror:1 row_mask:0xf bank_mask:0xf
	s_waitcnt lgkmcnt(0)
	v_add_f32_e32 v41, v41, v50
	v_fmamk_f32 v41, v41, 0x3a800000, v200
	v_mul_f32_e32 v50, 0x4b800000, v41
	v_cmp_gt_f32_e32 vcc, s38, v41
	s_nop 1
	v_cndmask_b32_e32 v41, v41, v50, vcc
	v_rsq_f32_e32 v41, v41
	s_nop 0
	v_mul_f32_e32 v50, 0x45800000, v41
	v_cndmask_b32_e32 v52, v41, v50, vcc
	v_mul_f32_e32 v22, v22, v52
	v_mul_f32_e32 v23, v23, v52
	v_mul_f32_e32 v24, v24, v52
	v_mul_f32_e32 v25, v25, v52
	v_mul_f32_e32 v22, v0, v22
	v_mul_f32_e32 v23, v1, v23
	v_mul_f32_e32 v24, v2, v24
	v_mul_f32_e32 v25, v3, v25
	s_waitcnt vmcnt(0)
	v_fma_f32 v21, v21, v22, v42
	v_fma_f32 v22, v38, v23, v43
	v_fma_f32 v23, v39, v24, v44
	v_fmac_f32_e32 v45, v40, v25
	v_cvt_pk_bf16_f32 v50, v21, v22
	v_cvt_pk_bf16_f32 v51, v23, v45
	global_load_dwordx4 v[22:25], v[4:5], off offset:1024
	global_load_dwordx4 v[38:41], v[46:47], off offset:1024
	global_load_dwordx4 v[42:45], v[48:49], off offset:1024
	v_mul_f32_e32 v21, v26, v52
	v_mul_f32_e32 v26, v27, v52
	v_mul_f32_e32 v27, v28, v52
	v_mul_f32_e32 v28, v29, v52
	global_store_dwordx2 v[12:13], v[50:51], off offset:-1024
	v_cmp_le_i32_e32 vcc, s73, v14
	s_or_b64 s[6:7], vcc, s[6:7]
	s_waitcnt vmcnt(3)
	v_mul_f32_e32 v21, v21, v22
	s_waitcnt vmcnt(2)
	v_add_f32_e32 v22, 1.0, v38
	v_mul_f32_e32 v23, v26, v23
	v_add_f32_e32 v26, 1.0, v39
	v_mul_f32_e32 v24, v27, v24
	v_add_f32_e32 v27, 1.0, v40
	v_mul_f32_e32 v25, v28, v25
	v_add_f32_e32 v28, 1.0, v41
	s_waitcnt vmcnt(1)
	v_fma_f32 v21, v21, v22, v42
	v_fma_f32 v22, v23, v26, v43
	v_fma_f32 v23, v24, v27, v44
	v_fmac_f32_e32 v45, v25, v28
	v_cvt_pk_bf16_f32 v42, v21, v22
	v_cvt_pk_bf16_f32 v43, v23, v45
	global_load_dwordx4 v[22:25], v[4:5], off offset:2048
	global_load_dwordx4 v[26:29], v[46:47], off offset:2048
	global_load_dwordx4 v[38:41], v[48:49], off offset:2048
	v_mul_f32_e32 v21, v30, v52
	v_mul_f32_e32 v30, v31, v52
	v_mul_f32_e32 v31, v32, v52
	v_mul_f32_e32 v32, v33, v52
	global_store_dwordx2 v[12:13], v[42:43], off offset:-512
	s_waitcnt vmcnt(3)
	v_mul_f32_e32 v21, v21, v22
	s_waitcnt vmcnt(2)
	v_add_f32_e32 v22, 1.0, v26
	v_mul_f32_e32 v23, v30, v23
	v_add_f32_e32 v26, 1.0, v27
	v_mul_f32_e32 v24, v31, v24
	v_add_f32_e32 v27, 1.0, v28
	v_mul_f32_e32 v25, v32, v25
	v_add_f32_e32 v28, 1.0, v29
	s_waitcnt vmcnt(1)
	v_fma_f32 v21, v21, v22, v38
	v_fma_f32 v22, v23, v26, v39
	v_fma_f32 v23, v24, v27, v40
	v_fmac_f32_e32 v41, v25, v28
	v_cvt_pk_bf16_f32 v38, v21, v22
	v_cvt_pk_bf16_f32 v39, v23, v41
	global_load_dwordx4 v[22:25], v[4:5], off offset:3072
	global_load_dwordx4 v[26:29], v[46:47], off offset:3072
	global_load_dwordx4 v[30:33], v[48:49], off offset:3072
	v_mul_f32_e32 v21, v34, v52
	v_mul_f32_e32 v34, v35, v52
	v_mul_f32_e32 v35, v36, v52
	v_mul_f32_e32 v36, v37, v52
	global_store_dwordx2 v[12:13], v[38:39], off
	s_waitcnt vmcnt(3)
	v_mul_f32_e32 v21, v21, v22
	s_waitcnt vmcnt(2)
	v_add_f32_e32 v22, 1.0, v26
	v_mul_f32_e32 v23, v34, v23
	v_add_f32_e32 v26, 1.0, v27
	v_mul_f32_e32 v24, v35, v24
	v_add_f32_e32 v27, 1.0, v28
	v_mul_f32_e32 v25, v36, v25
	v_add_f32_e32 v28, 1.0, v29
	s_waitcnt vmcnt(1)
	v_fma_f32 v21, v21, v22, v30
	v_fma_f32 v22, v23, v26, v31
	v_fma_f32 v23, v24, v27, v32
	v_fmac_f32_e32 v33, v25, v28
	v_cvt_pk_bf16_f32 v22, v21, v22
	v_cvt_pk_bf16_f32 v23, v23, v33
	global_store_dwordx2 v[12:13], v[22:23], off offset:512
	v_lshl_add_u64 v[12:13], v[12:13], 0, s[40:41]
	s_andn2_b64 exec, exec, s[6:7]
	s_cbranch_execnz .LBB0_433

.LBB0_1670:
	s_or_b64 exec, exec, s[12:13]
	v_add_co_u32_e32 v38, vcc, 0x15c6c000, v38
	s_mov_b32 s0, 0x15c6c000
	s_nop 0
	v_addc_co_u32_e32 v39, vcc, 0, v39, vcc
	global_load_dwordx4 v[46:49], v[38:39], off
	global_load_dwordx4 v[50:53], v[38:39], off offset:1024
	s_waitcnt vmcnt(1)
	v_lshlrev_b32_e32 v42, 16, v46
	v_mul_f32_e32 v42, v0, v42
	s_waitcnt vmcnt(0)
	v_lshlrev_b32_e32 v43, 16, v50
	v_fmac_f32_e32 v32, v42, v43
	v_and_b32_e32 v42, 0xffff0000, v46
	v_mul_f32_e32 v42, v1, v42
	v_and_b32_e32 v43, 0xffff0000, v50
	v_fmac_f32_e32 v33, v42, v43
	v_lshlrev_b32_e32 v42, 16, v47
	v_mul_f32_e32 v42, v2, v42
	v_lshlrev_b32_e32 v43, 16, v51
	v_fmac_f32_e32 v34, v42, v43
	v_and_b32_e32 v42, 0xffff0000, v47
	v_mul_f32_e32 v42, v3, v42
	v_and_b32_e32 v43, 0xffff0000, v51
	v_fmac_f32_e32 v35, v42, v43
	v_lshlrev_b32_e32 v42, 16, v48
	v_mul_f32_e32 v42, v4, v42
	v_lshlrev_b32_e32 v43, 16, v52
	v_fmac_f32_e32 v36, v42, v43
	v_and_b32_e32 v42, 0xffff0000, v48
	v_mul_f32_e32 v42, v5, v42
	v_and_b32_e32 v43, 0xffff0000, v52
	v_fmac_f32_e32 v37, v42, v43
	v_lshlrev_b32_e32 v42, 16, v49
	v_mul_f32_e32 v42, v6, v42
	v_lshlrev_b32_e32 v43, 16, v53
	v_fmac_f32_e32 v40, v42, v43
	v_and_b32_e32 v42, 0xffff0000, v49
	global_load_dwordx4 v[46:49], v[38:39], off offset:2048
	v_mul_f32_e32 v42, v7, v42
	v_and_b32_e32 v43, 0xffff0000, v53
	v_fmac_f32_e32 v41, v42, v43
	s_waitcnt vmcnt(0)
	v_lshlrev_b32_e32 v38, 16, v46
	v_mul_f32_e32 v32, v32, v38
	v_and_b32_e32 v38, 0xffff0000, v46
	v_mul_f32_e32 v33, v33, v38
	v_cvt_pk_bf16_f32 v32, v32, v33
	v_lshlrev_b32_e32 v33, 16, v47
	v_mul_f32_e32 v33, v34, v33
	v_and_b32_e32 v34, 0xffff0000, v47
	v_mul_f32_e32 v34, v35, v34
	v_cvt_pk_bf16_f32 v33, v33, v34
	v_lshlrev_b32_e32 v34, 16, v48
	v_and_b32_e32 v35, 0xffff0000, v48
	v_mul_f32_e32 v34, v36, v34
	v_mul_f32_e32 v35, v37, v35
	v_cvt_pk_bf16_f32 v34, v34, v35
	v_lshlrev_b32_e32 v35, 16, v49
	v_and_b32_e32 v36, 0xffff0000, v49
	v_mul_f32_e32 v35, v40, v35
	v_mul_f32_e32 v36, v41, v36
	v_cvt_pk_bf16_f32 v35, v35, v36
	v_lshl_add_u64 v[36:37], v[28:29], 0, v[10:11]
	global_store_dwordx4 v[36:37], v[32:35], off
	s_nop 1
	v_lshl_add_u64 v[32:33], v[18:19], 0, v[92:93]
	v_add_co_u32_e32 v32, vcc, s0, v32
	s_nop 1
	v_addc_co_u32_e32 v33, vcc, 0, v33, vcc
	global_load_dwordx2 v[32:33], v[32:33], off offset:3072
	v_cmp_lt_i32_e32 vcc, v204, v198
	s_waitcnt vmcnt(0)
	v_lshlrev_b32_e32 v40, 16, v32
	v_and_b32_e32 v41, 0xffff0000, v32
	v_pk_mul_f32 v[34:35], v[40:41], v[40:41]
	v_and_b32_e32 v42, 0xffff0000, v33
	v_lshlrev_b32_e32 v43, 16, v33
	v_pk_mul_f32 v[32:33], v[42:43], v[42:43]
	v_add_f32_e32 v34, v34, v35
	v_add_f32_e32 v33, v33, v34
	v_add_f32_e32 v33, v32, v33
	v_cndmask_b32_e32 v32, v197, v204, vcc
	v_lshlrev_b32_e32 v32, 2, v32
	v_mov_b32_e32 v34, v33
	s_nop 1
	v_permlane32_swap_b32_e32 v34, v33
	v_cmp_lt_i32_e32 vcc, v205, v198
	s_waitcnt lgkmcnt(0)
	v_add_f32_e32 v34, v33, v34
	v_cndmask_b32_e32 v33, v197, v205, vcc
	v_lshlrev_b32_e32 v33, 2, v33
	v_mov_b32_e32 v35, v34
	s_nop 1
	v_permlane16_swap_b32_e32 v35, v34
	v_cmp_lt_i32_e32 vcc, v203, v198
	s_waitcnt lgkmcnt(0)
	v_add_f32_e32 v35, v34, v35
	v_cndmask_b32_e32 v34, v197, v203, vcc
	v_lshlrev_b32_e32 v34, 2, v34
	s_nop 1
	v_mov_b32_dpp v36, v35 row_ror:8 row_mask:0xf bank_mask:0xf
	v_cmp_lt_i32_e32 vcc, v202, v198
	s_waitcnt lgkmcnt(0)
	v_add_f32_e32 v36, v35, v36
	v_cndmask_b32_e32 v35, v197, v202, vcc
	v_lshlrev_b32_e32 v35, 2, v35
	s_nop 1
	v_mov_b32_dpp v37, v36 row_ror:4 row_mask:0xf bank_mask:0xf
	v_cmp_lt_i32_e32 vcc, v201, v198
	s_waitcnt lgkmcnt(0)
	v_add_f32_e32 v36, v36, v37
	v_cndmask_b32_e32 v37, v197, v201, vcc
	v_lshlrev_b32_e32 v45, 2, v37
	s_nop 1
	v_mov_b32_dpp v37, v36 row_ror:2 row_mask:0xf bank_mask:0xf
	v_cmp_lt_i32_e32 vcc, v199, v198
	s_waitcnt lgkmcnt(0)
	v_add_f32_e32 v36, v36, v37
	v_cndmask_b32_e32 v37, v197, v199, vcc
	v_lshlrev_b32_e32 v46, 2, v37
	s_nop 1
	v_mov_b32_dpp v37, v36 row_ror:1 row_mask:0xf bank_mask:0xf
	s_waitcnt lgkmcnt(0)
	v_add_f32_e32 v36, v36, v37
	v_fmamk_f32 v36, v36, 0x3b800000, v200
	v_cmp_gt_f32_e32 vcc, s38, v36
	v_mul_f32_e32 v37, 0x4b800000, v36
	s_nop 0
	v_cndmask_b32_e32 v36, v36, v37, vcc
	v_rsq_f32_e32 v36, v36
	s_nop 0
	v_mul_f32_e32 v37, 0x45800000, v36
	v_cndmask_b32_e32 v47, v36, v37, vcc
	global_load_dwordx4 v[36:39], v[12:13], off
	v_mul_f32_e32 v40, v47, v40
	s_waitcnt vmcnt(0)
	v_mul_f32_e32 v36, v36, v40
	v_mul_f32_e32 v40, v47, v41
	v_mul_f32_e32 v37, v37, v40
	v_cvt_pk_bf16_f32 v36, v36, v37
	v_mul_f32_e32 v37, v47, v43
	v_mul_f32_e32 v37, v38, v37
	v_mul_f32_e32 v38, v47, v42
	v_mul_f32_e32 v38, v39, v38
	v_cvt_pk_bf16_f32 v37, v37, v38
	global_store_dwordx2 v[26:27], v[36:37], off
	v_lshl_add_u64 v[36:37], v[18:19], 0, v[30:31]
	global_load_dword v37, v[36:37], off
	s_waitcnt vmcnt(0)
	v_lshlrev_b32_e32 v36, 16, v37
	v_and_b32_e32 v37, 0xffff0000, v37
	v_pk_mul_f32 v[38:39], v[36:37], v[36:37]
	s_nop 0
	v_add_f32_e32 v38, v38, v39
	v_mov_b32_e32 v32, v38
	s_nop 1
	v_permlane32_swap_b32_e32 v32, v38
	s_waitcnt lgkmcnt(0)
	v_add_f32_e32 v32, v38, v32
	v_mov_b32_e32 v33, v32
	s_nop 1
	v_permlane16_swap_b32_e32 v33, v32
	s_waitcnt lgkmcnt(0)
	v_add_f32_e32 v32, v32, v33
	s_nop 1
	v_mov_b32_dpp v33, v32 row_ror:8 row_mask:0xf bank_mask:0xf
	s_waitcnt lgkmcnt(0)
	v_add_f32_e32 v32, v32, v33
	s_nop 1
	v_mov_b32_dpp v33, v32 row_ror:4 row_mask:0xf bank_mask:0xf
	s_waitcnt lgkmcnt(0)
	v_add_f32_e32 v32, v32, v33
	s_nop 1
	v_mov_b32_dpp v33, v32 row_ror:2 row_mask:0xf bank_mask:0xf
	s_waitcnt lgkmcnt(0)
	v_add_f32_e32 v32, v32, v33
	s_nop 1
	v_mov_b32_dpp v33, v32 row_ror:1 row_mask:0xf bank_mask:0xf
	s_waitcnt lgkmcnt(0)
	v_add_f32_e32 v32, v32, v33
	v_fmamk_f32 v32, v32, 0x3c000000, v200
	v_cmp_gt_f32_e32 vcc, s38, v32
	v_mul_f32_e32 v33, 0x4b800000, v32
	s_nop 0
	v_cndmask_b32_e32 v32, v32, v33, vcc
	v_rsq_f32_e32 v32, v32
	s_nop 0
	v_mul_f32_e32 v33, 0x45800000, v32
	v_cndmask_b32_e32 v34, v32, v33, vcc
	global_load_dwordx2 v[32:33], v[16:17], off
	v_mul_f32_e32 v35, v34, v36
	v_mul_f32_e32 v34, v34, v37
	s_waitcnt vmcnt(0)
	v_mul_f32_e32 v32, v32, v35
	v_mul_f32_e32 v33, v33, v34
	v_cvt_pk_bf16_f32 v32, v32, v33
	global_store_dword v[24:25], v32, off
	s_and_saveexec_b64 s[12:13], s[4:5]
	s_cbranch_execz .LBB0_1665
	v_lshl_add_u64 v[32:33], v[18:19], 0, v[14:15]
	v_add_co_u32_e32 v32, vcc, 0x15c6c000, v32
	s_nop 1
	v_addc_co_u32_e32 v33, vcc, 0, v33, vcc
	global_load_ushort v34, v[32:33], off offset:3840
	s_waitcnt vmcnt(0)
	v_lshlrev_b32_e32 v34, 16, v34
	global_load_ushort v32, v[32:33], off offset:3872
	s_waitcnt vmcnt(0)
	v_lshlrev_b32_e32 v35, 16, v32
	v_lshl_add_u64 v[32:33], s[6:7], 0, v[22:23]
	global_load_dword v36, v[32:33], off
	v_lshl_add_u64 v[32:33], s[8:9], 0, v[22:23]
	global_load_dword v32, v[32:33], off
	s_waitcnt vmcnt(0)
	v_mul_f32_e32 v33, v32, v35
	v_mul_f32_e32 v35, v36, v35
	v_fma_f32 v33, v36, v34, -v33
	v_fmac_f32_e32 v35, v32, v34
	v_cvt_pk_bf16_f32 v32, v33, v35
	global_store_dword v[20:21], v32, off offset:-768
	global_store_dword v[20:21], v32, off offset:-576
	global_store_dword v[20:21], v32, off offset:-384
	global_store_dword v[20:21], v32, off offset:-192
	global_store_dword v[20:21], v32, off
	global_store_dword v[20:21], v32, off offset:192
	global_store_dword v[20:21], v32, off offset:384
	global_store_dword v[20:21], v32, off offset:576
	s_branch .LBB0_1665

.LBB0_2154:
	v_lshl_add_u64 v[46:47], v[18:19], 0, v[16:17]
	global_load_dwordx4 v[30:33], v[46:47], off offset:-2048
	global_load_dwordx4 v[34:37], v[46:47], off offset:-1024
	global_load_dwordx4 v[38:41], v[46:47], off
	global_load_dwordx4 v[42:45], v[46:47], off offset:1024
	v_add_u32_e32 v22, s30, v22
	v_cmp_le_i32_e32 vcc, s73, v22
	s_or_b64 s[0:1], vcc, s[0:1]
	v_lshl_add_u64 v[46:47], v[20:21], 0, v[16:17]
	v_lshl_add_u64 v[18:19], v[18:19], 0, s[34:35]
	v_lshl_add_u64 v[20:21], v[20:21], 0, s[34:35]
	s_waitcnt vmcnt(3)
	v_mov_b32_e32 v50, v31
	s_waitcnt vmcnt(2)
	v_mov_b32_e32 v51, v35
	v_mov_b32_e32 v48, v30
	v_mov_b32_e32 v49, v34
	s_waitcnt vmcnt(1)
	v_mov_b32_e32 v58, v39
	s_waitcnt vmcnt(0)
	v_mov_b32_e32 v59, v43
	v_pk_mul_f32 v[50:51], v[50:51], v[50:51]
	v_mov_b32_e32 v52, v32
	v_mov_b32_e32 v53, v36
	v_mov_b32_e32 v56, v38
	v_mov_b32_e32 v57, v42
	v_pk_mul_f32 v[58:59], v[58:59], v[58:59]
	v_pk_fma_f32 v[48:49], v[48:49], v[48:49], v[50:51]
	v_mov_b32_e32 v54, v33
	v_mov_b32_e32 v55, v37
	v_mov_b32_e32 v60, v40
	v_mov_b32_e32 v61, v44
	v_pk_fma_f32 v[50:51], v[56:57], v[56:57], v[58:59]
	v_pk_fma_f32 v[48:49], v[52:53], v[52:53], v[48:49]
	v_mov_b32_e32 v62, v41
	v_mov_b32_e32 v63, v45
	v_pk_fma_f32 v[50:51], v[60:61], v[60:61], v[50:51]
	v_pk_fma_f32 v[48:49], v[54:55], v[54:55], v[48:49]
	v_pk_fma_f32 v[50:51], v[62:63], v[62:63], v[50:51]
	v_add_f32_e32 v48, v48, v49
	v_add_f32_e32 v48, v48, v50
	v_add_f32_e32 v48, v48, v51
	v_mov_b32_e32 v49, v48
	s_nop 1
	v_permlane32_swap_b32_e32 v49, v48
	s_waitcnt lgkmcnt(0)
	v_add_f32_e32 v48, v48, v49
	v_mov_b32_e32 v49, v48
	s_nop 1
	v_permlane16_swap_b32_e32 v49, v48
	s_waitcnt lgkmcnt(0)
	v_add_f32_e32 v48, v48, v49
	s_nop 1
	v_mov_b32_dpp v49, v48 row_ror:8 row_mask:0xf bank_mask:0xf
	s_waitcnt lgkmcnt(0)
	v_add_f32_e32 v48, v48, v49
	s_nop 1
	v_mov_b32_dpp v49, v48 row_ror:4 row_mask:0xf bank_mask:0xf
	s_waitcnt lgkmcnt(0)
	v_add_f32_e32 v48, v48, v49
	s_nop 1
	v_mov_b32_dpp v49, v48 row_ror:2 row_mask:0xf bank_mask:0xf
	s_waitcnt lgkmcnt(0)
	v_add_f32_e32 v48, v48, v49
	s_nop 1
	v_mov_b32_dpp v49, v48 row_ror:1 row_mask:0xf bank_mask:0xf
	s_waitcnt lgkmcnt(0)
	v_add_f32_e32 v48, v48, v49
	v_fmamk_f32 v48, v48, 0x3a800000, v29
	v_mul_f32_e32 v49, 0x4b800000, v48
	v_cmp_gt_f32_e32 vcc, s2, v48
	s_nop 1
	v_cndmask_b32_e32 v48, v48, v49, vcc
	v_rsq_f32_e32 v48, v48
	s_nop 0
	v_mul_f32_e32 v49, 0x45800000, v48
	v_cndmask_b32_e32 v48, v48, v49, vcc
	v_pk_mul_f32 v[30:31], v[30:31], v[48:49] op_sel_hi:[1,0]
	v_pk_mul_f32 v[32:33], v[32:33], v[48:49] op_sel_hi:[1,0]
	v_pk_mul_f32 v[34:35], v[34:35], v[48:49] op_sel_hi:[1,0]
	v_pk_mul_f32 v[36:37], v[36:37], v[48:49] op_sel_hi:[1,0]
	v_pk_mul_f32 v[38:39], v[38:39], v[48:49] op_sel_hi:[1,0]
	v_pk_mul_f32 v[40:41], v[40:41], v[48:49] op_sel_hi:[1,0]
	v_pk_mul_f32 v[42:43], v[42:43], v[48:49] op_sel_hi:[1,0]
	v_pk_mul_f32 v[44:45], v[44:45], v[48:49] op_sel_hi:[1,0]
	v_pk_mul_f32 v[30:31], v[0:1], v[30:31]
	v_pk_mul_f32 v[32:33], v[2:3], v[32:33]
	v_pk_mul_f32 v[34:35], v[4:5], v[34:35]
	v_pk_mul_f32 v[36:37], v[6:7], v[36:37]
	v_pk_mul_f32 v[38:39], v[8:9], v[38:39]
	v_pk_mul_f32 v[40:41], v[10:11], v[40:41]
	v_pk_mul_f32 v[42:43], v[12:13], v[42:43]
	v_pk_mul_f32 v[44:45], v[14:15], v[44:45]
	global_store_dwordx4 v[46:47], v[30:33], off
	global_store_dwordx4 v[46:47], v[34:37], off offset:1024
	global_store_dwordx4 v[46:47], v[38:41], off offset:2048
	global_store_dwordx4 v[46:47], v[42:45], off offset:3072
	s_andn2_b64 exec, exec, s[0:1]
	s_cbranch_execnz .LBB0_2154
